# static s_setprio 1 for waves 4-7 during the three attention phases (strategy: static priority raise for the younger half); on top of v022
# baseline (speedup 1.0000x reference)
.LBB0_452:
	s_ashr_i32 s5, s5, 6
	s_mul_i32 s0, s5, 0x1400
	s_add_i32 s0, s0, 0
	v_bfe_u32 v162, v4, 3, 3
	s_add_i32 s18, s0, 0x1b000
	s_ashr_i32 s64, s2, 11
	v_lshlrev_b32_e32 v6, s4, v162
	s_add_u32 s0, s22, s6
	s_addc_u32 s1, s23, 0
	v_lshl_or_b32 v88, v6, 7, v161
	v_mov_b32_e32 v89, 0
	s_lshl_b32 s62, s5, 5
	v_lshl_add_u64 v[6:7], s[0:1], 0, v[88:89]
	s_add_i32 s0, s62, s95
	s_or_b32 s6, s0, 24
	s_ashr_i32 s7, s6, 31
	s_lshl_b64 s[6:7], s[6:7], s4
	s_add_u32 s6, s6, s61
	s_addc_u32 s7, s7, 0
	s_lshl_b64 s[6:7], s[6:7], 7
	v_lshl_add_u64 v[8:9], v[6:7], 0, s[6:7]
	s_or_b32 s6, s0, 16
	s_ashr_i32 s7, s6, 31
	s_lshl_b64 s[6:7], s[6:7], s4
	s_add_u32 s6, s6, s61
	s_addc_u32 s7, s7, 0
	s_lshl_b64 s[6:7], s[6:7], 7
	v_lshl_add_u64 v[10:11], v[6:7], 0, s[6:7]
	s_or_b32 s6, s0, 8
	s_ashr_i32 s7, s6, 31
	s_lshl_b64 s[6:7], s[6:7], s4
	s_add_u32 s6, s6, s61
	s_addc_u32 s7, s7, 0
	s_ashr_i32 s1, s0, 31
	s_lshl_b64 s[6:7], s[6:7], 7
	s_lshl_b64 s[0:1], s[0:1], s4
	s_add_u32 s0, s0, s61
	s_addc_u32 s1, s1, 0
	s_lshl_b64 s[0:1], s[0:1], 7
	global_load_dwordx4 v[140:143], v[8:9], off
	global_load_dwordx4 v[144:147], v[10:11], off
	v_lshl_add_u64 v[8:9], v[6:7], 0, s[6:7]
	v_lshl_add_u64 v[6:7], v[6:7], 0, s[0:1]
	s_or_b32 s0, s95, 0xc0
	s_mov_b32 s1, s17
	s_lshl_b64 s[0:1], s[0:1], s4
	s_add_u32 s0, s0, s61
	s_addc_u32 s1, s1, 0
	s_lshl_b64 s[0:1], s[0:1], 7
	global_load_dwordx4 v[132:135], v[8:9], off
	global_load_dwordx4 v[136:139], v[6:7], off
	v_lshl_add_u64 v[6:7], v[0:1], 0, s[0:1]
	v_lshl_add_u64 v[8:9], v[2:3], 0, s[0:1]
	s_or_b32 s0, s95, 0x80
	s_mov_b32 s1, s17
	s_lshl_b64 s[0:1], s[0:1], s4
	s_add_u32 s0, s0, s61
	s_addc_u32 s1, s1, 0
	s_lshl_b64 s[0:1], s[0:1], 7
	global_load_dwordx4 v[128:131], v[6:7], off nt
	global_load_dwordx4 v[116:119], v[8:9], off nt
	v_lshl_add_u64 v[6:7], v[2:3], 0, s[0:1]
	v_lshl_add_u64 v[8:9], v[0:1], 0, s[0:1]
	s_or_b32 s0, s95, 64
	s_mov_b32 s1, s17
	s_lshl_b64 s[0:1], s[0:1], s4
	s_add_u32 s0, s0, s61
	s_addc_u32 s1, s1, 0
	s_lshl_b64 s[0:1], s[0:1], 7
	global_load_dwordx4 v[108:111], v[6:7], off nt
	global_load_dwordx4 v[124:127], v[8:9], off nt
	v_lshl_add_u64 v[6:7], v[2:3], 0, s[0:1]
	v_lshl_add_u64 v[8:9], v[0:1], 0, s[0:1]
	s_lshl_b32 s0, s95, s4
	s_add_i32 s0, s0, s61
	s_lshl_b32 s0, s0, 7
	s_mov_b32 s1, s17
	v_lshl_add_u64 v[2:3], v[2:3], 0, s[0:1]
	global_load_dwordx4 v[112:115], v[6:7], off nt
	global_load_dwordx4 v[120:123], v[8:9], off nt
	v_lshl_add_u64 v[0:1], v[0:1], 0, s[0:1]
	global_load_dwordx4 v[100:103], v[2:3], off nt
	global_load_dwordx4 v[104:107], v[0:1], off nt
	v_and_b32_e32 v163, 31, v4
	v_bfe_u32 v12, v4, 5, 1
	s_movk_i32 s0, 0x90
	v_mov_b32_e32 v2, s18
	v_mad_u32_u24 v166, v163, s0, v2
	v_or_b32_e32 v2, 0x80, v163
	v_lshlrev_b32_e32 v3, 2, v12
	v_bfe_u32 v6, v4, 2, 2
	v_and_b32_e32 v5, 63, v4
	v_sub_u32_e32 v168, v2, v3
	v_or3_b32 v3, v6, v3, s62
	v_and_b32_e32 v6, 16, v4
	v_lshlrev_b32_e32 v4, 2, v4
	s_add_i32 s1, s62, 32
	v_and_or_b32 v4, v4, 12, v6
	v_or_b32_e32 v6, s1, v163
	s_add_i32 s1, s62, 64
	v_or_b32_e32 v7, s1, v163
	s_add_i32 s1, s62, 0x60
	v_or_b32_e32 v8, s1, v163
	s_add_i32 s1, s62, 0x80
	v_add_u32_e32 v164, 0, v161
	v_lshlrev_b32_e32 v167, 4, v12
	v_mul_lo_u32 v3, v3, s0
	v_lshlrev_b32_e32 v4, 1, v4
	v_cmp_gt_u32_e64 s[4:5], 32, v5
	v_or_b32_e32 v5, s62, v163
	v_or_b32_e32 v9, s1, v163
	v_add_u32_e32 v0, 0xd800, v164
	v_add_u32_e32 v1, s18, v161
	v_add_u32_e32 v2, 0, v167
	v_add3_u32 v169, 0, v3, v4
	v_mul_i32_i24_e32 v3, 0xffffff74, v163
	v_mul_lo_u32 v171, v160, s0
	v_mul_u32_u24_e32 v4, 0x90, v162
	v_mul_lo_u32 v5, v5, s0
	v_mul_lo_u32 v6, v6, s0
	v_mul_lo_u32 v7, v7, s0
	v_mul_lo_u32 v8, v8, s0
	v_mul_lo_u32 v9, v9, s0
	v_mul_u32_u24_e32 v10, 0x240, v12
	v_lshlrev_b32_e32 v11, 1, v163
	s_mov_b32 s36, 2.0
	s_mov_b32 s44, 0x41000000
	s_mov_b32 s46, 0x41200000
	s_mov_b32 s48, 0x41800000
	s_mov_b32 s52, 0x41900000
	s_mov_b32 s54, 0x41c00000
	s_mov_b32 s56, 0x41d00000
	v_lshlrev_b32_e32 v165, 11, v162
	v_add_u32_e32 v170, 0xd800, v169
	v_add3_u32 v172, s18, v10, v11
	v_lshl_add_u32 v173, v162, 2, s18
	v_add_u32_e32 v174, v0, v171
	v_add_u32_e32 v175, v2, v5
	v_add_u32_e32 v176, v2, v6
	v_add_u32_e32 v177, v2, v7
	v_add_u32_e32 v178, v2, v8
	v_add_u32_e32 v179, v2, v9
	s_mov_b32 s37, 0x40400000
	s_mov_b32 s45, 0x41100000
	s_mov_b32 s47, 0x41300000
	s_mov_b32 s49, 0x41880000
	s_mov_b32 s53, 0x41980000
	s_mov_b32 s55, 0x41c80000
	s_mov_b32 s57, 0x41d80000
	s_movk_i32 s65, 0x83
	s_movk_i32 s66, 0x84
	s_movk_i32 s67, 0x89
	s_movk_i32 s68, 0x87
	s_movk_i32 s69, 0x8a
	s_movk_i32 s70, 0x8b
	s_movk_i32 s71, 0x8c
	s_movk_i32 s72, 0x91
	s_movk_i32 s73, 0x8f
	s_movk_i32 s74, 0x92
	s_movk_i32 s75, 0x93
	s_movk_i32 s76, 0x94
	s_movk_i32 s77, 0x99
	s_movk_i32 s82, 0x97
	s_movk_i32 s83, 0x9a
	s_movk_i32 s84, 0x9b
	s_movk_i32 s85, 0x9c
	v_mbcnt_hi_u32_b32 v181, -1, v183
	v_add_u32_e32 v184, v166, v3
	s_mov_b32 s86, 0x1b200000
	s_mov_b32 s87, 0x45800000
	v_add_u32_e32 v185, v1, v4
	v_mov_b32_e32 v186, 0x42800000
	v_mov_b32_e32 v187, 0xff800000
	s_mov_b32 s88, s2
	s_mov_b32 s94, s64
	s_mov_b32 s91, s95
	s_mov_b32 s90, s61
	s_mov_b32 s89, s60
	s_mov_b32 s92, s63
	s_waitcnt vmcnt(0)
	s_bitcmp1_b32 s33, 2
	s_cbranch_scc0 .Lprio_0
	s_setprio 1
.Lprio_0:
	s_branch .LBB0_454
.LBB0_453:
	s_or_b64 exec, exec, s[0:1]
	s_nop 15
	s_nop 7
	s_nop 15
	s_nop 7
	v_cvt_pk_bf16_f32 v0, v0, v16
	s_nop 4
	ds_write_b16 v172, v0
	ds_write_b16_d16_hi v172, v0 offset:64
	v_cvt_pk_bf16_f32 v0, v1, v17
	ds_write_b16 v172, v0 offset:144
	ds_write_b16_d16_hi v172, v0 offset:208
	v_cvt_pk_bf16_f32 v0, v2, v18
	ds_write_b16 v172, v0 offset:288
	ds_write_b16_d16_hi v172, v0 offset:352
	v_cvt_pk_bf16_f32 v0, v3, v19
	ds_write_b16 v172, v0 offset:432
	ds_write_b16_d16_hi v172, v0 offset:496
	v_cvt_pk_bf16_f32 v0, v4, v20
	ds_write_b16 v172, v0 offset:1152
	ds_write_b16_d16_hi v172, v0 offset:1216
	v_cvt_pk_bf16_f32 v0, v5, v21
	ds_write_b16 v172, v0 offset:1296
	ds_write_b16_d16_hi v172, v0 offset:1360
	v_cvt_pk_bf16_f32 v0, v6, v22
	ds_write_b16 v172, v0 offset:1440
	ds_write_b16_d16_hi v172, v0 offset:1504
	v_cvt_pk_bf16_f32 v0, v7, v23
	ds_write_b16 v172, v0 offset:1584
	ds_write_b16_d16_hi v172, v0 offset:1648
	v_cvt_pk_bf16_f32 v0, v8, v24
	ds_write_b16 v172, v0 offset:2304
	ds_write_b16_d16_hi v172, v0 offset:2368
	v_cvt_pk_bf16_f32 v0, v9, v25
	ds_write_b16 v172, v0 offset:2448
	ds_write_b16_d16_hi v172, v0 offset:2512
	v_cvt_pk_bf16_f32 v0, v10, v26
	ds_write_b16 v172, v0 offset:2592
	ds_write_b16_d16_hi v172, v0 offset:2656
	v_cvt_pk_bf16_f32 v0, v11, v27
	s_lshl_b32 s7, s63, 7
	ds_write_b16 v172, v0 offset:2736
	ds_write_b16_d16_hi v172, v0 offset:2800
	v_cvt_pk_bf16_f32 v0, v12, v28
	ds_write_b16 v172, v0 offset:3456
	ds_write_b16_d16_hi v172, v0 offset:3520
	v_cvt_pk_bf16_f32 v0, v13, v29
	s_cmp_eq_u32 s64, 0
	ds_write_b16 v172, v0 offset:3600
	ds_write_b16_d16_hi v172, v0 offset:3664
	v_cvt_pk_bf16_f32 v0, v14, v30
	s_cselect_b32 s18, s39, s25
	s_cselect_b32 s19, s38, s24
	s_lshl_b64 s[0:1], s[16:17], 23
	ds_write_b16 v172, v0 offset:3744
	ds_write_b16_d16_hi v172, v0 offset:3808
	v_cvt_pk_bf16_f32 v0, v15, v31
	s_add_u32 s0, s19, s0
	ds_write_b16 v172, v0 offset:3888
	ds_write_b16_d16_hi v172, v0 offset:3952
	s_addc_u32 s1, s18, s1
	s_waitcnt lgkmcnt(0)
	s_add_u32 s0, s0, s7
	v_or_b32_e32 v88, v88, v161
	s_addc_u32 s1, s1, 0
	ds_read_b32 v6, v173 offset:4608
	ds_read_b128 v[0:3], v185
	v_lshl_add_u64 v[4:5], s[0:1], 0, v[88:89]
	s_ashr_i32 s0, s6, 31
	s_mul_hi_u32 s1, s60, s6
	s_mul_i32 s7, s0, s60
	s_add_i32 s1, s1, s7
	s_mul_i32 s0, s60, s6
	s_add_u32 s0, s0, s61
	s_addc_u32 s1, s1, 0
	s_waitcnt lgkmcnt(0)
	v_lshlrev_b32_e32 v7, 16, v0
	v_and_b32_e32 v0, 0xffff0000, v0
	v_mul_f32_e32 v7, v6, v7
	v_mul_f32_e32 v0, v6, v0
	v_lshlrev_b32_e32 v8, 16, v1
	v_and_b32_e32 v1, 0xffff0000, v1
	v_lshlrev_b32_e32 v9, 16, v2
	v_and_b32_e32 v2, 0xffff0000, v2
	v_lshlrev_b32_e32 v10, 16, v3
	v_and_b32_e32 v3, 0xffff0000, v3
	s_lshl_b64 s[0:1], s[0:1], 11
	v_mul_f32_e32 v8, v6, v8
	v_mul_f32_e32 v1, v6, v1
	v_mul_f32_e32 v9, v6, v9
	v_mul_f32_e32 v2, v6, v2
	v_mul_f32_e32 v10, v6, v10
	v_mul_f32_e32 v3, v6, v3
	v_cvt_pk_bf16_f32 v0, v7, v0
	v_lshl_add_u64 v[6:7], v[4:5], 0, s[0:1]
	v_cvt_pk_bf16_f32 v1, v8, v1
	v_cvt_pk_bf16_f32 v2, v9, v2
	v_cvt_pk_bf16_f32 v3, v10, v3
	global_store_dwordx4 v[6:7], v[0:3], off
	ds_read_b32 v6, v173 offset:4640
	ds_read_b128 v[0:3], v185 offset:1152
	s_or_b32 s0, s6, 8
	s_mul_hi_u32 s1, s0, s60
	s_add_i32 s1, s1, s7
	s_mul_i32 s0, s0, s60
	s_add_u32 s0, s0, s61
	s_addc_u32 s1, s1, 0
	s_waitcnt lgkmcnt(0)
	v_lshlrev_b32_e32 v7, 16, v0
	v_and_b32_e32 v0, 0xffff0000, v0
	v_mul_f32_e32 v7, v6, v7
	v_mul_f32_e32 v0, v6, v0
	v_lshlrev_b32_e32 v8, 16, v1
	v_and_b32_e32 v1, 0xffff0000, v1
	v_lshlrev_b32_e32 v9, 16, v2
	v_and_b32_e32 v2, 0xffff0000, v2
	v_lshlrev_b32_e32 v10, 16, v3
	v_and_b32_e32 v3, 0xffff0000, v3
	s_lshl_b64 s[0:1], s[0:1], 11
	v_mul_f32_e32 v8, v6, v8
	v_mul_f32_e32 v1, v6, v1
	v_mul_f32_e32 v9, v6, v9
	v_mul_f32_e32 v2, v6, v2
	v_mul_f32_e32 v10, v6, v10
	v_mul_f32_e32 v3, v6, v3
	v_cvt_pk_bf16_f32 v0, v7, v0
	v_lshl_add_u64 v[6:7], v[4:5], 0, s[0:1]
	v_cvt_pk_bf16_f32 v1, v8, v1
	v_cvt_pk_bf16_f32 v2, v9, v2
	v_cvt_pk_bf16_f32 v3, v10, v3
	global_store_dwordx4 v[6:7], v[0:3], off
	ds_read_b32 v6, v173 offset:4672
	ds_read_b128 v[0:3], v185 offset:2304
	s_or_b32 s0, s6, 16
	s_mul_hi_u32 s1, s0, s60
	s_add_i32 s1, s1, s7
	s_mul_i32 s0, s0, s60
	s_add_u32 s0, s0, s61
	s_addc_u32 s1, s1, 0
	s_waitcnt lgkmcnt(0)
	v_lshlrev_b32_e32 v7, 16, v0
	v_and_b32_e32 v0, 0xffff0000, v0
	v_mul_f32_e32 v7, v6, v7
	v_mul_f32_e32 v0, v6, v0
	v_lshlrev_b32_e32 v8, 16, v1
	v_and_b32_e32 v1, 0xffff0000, v1
	v_lshlrev_b32_e32 v9, 16, v2
	v_and_b32_e32 v2, 0xffff0000, v2
	v_lshlrev_b32_e32 v10, 16, v3
	v_and_b32_e32 v3, 0xffff0000, v3
	s_lshl_b64 s[0:1], s[0:1], 11
	v_mul_f32_e32 v8, v6, v8
	v_mul_f32_e32 v1, v6, v1
	v_mul_f32_e32 v9, v6, v9
	v_mul_f32_e32 v2, v6, v2
	v_mul_f32_e32 v10, v6, v10
	v_mul_f32_e32 v3, v6, v3
	v_cvt_pk_bf16_f32 v0, v7, v0
	v_lshl_add_u64 v[6:7], v[4:5], 0, s[0:1]
	v_cvt_pk_bf16_f32 v1, v8, v1
	v_cvt_pk_bf16_f32 v2, v9, v2
	v_cvt_pk_bf16_f32 v3, v10, v3
	global_store_dwordx4 v[6:7], v[0:3], off
	s_or_b32 s0, s6, 24
	ds_read_b32 v6, v173 offset:4704
	ds_read_b128 v[0:3], v185 offset:3456
	s_mul_hi_u32 s1, s0, s60
	s_add_i32 s1, s1, s7
	s_mul_i32 s0, s0, s60
	s_add_u32 s0, s0, s61
	s_addc_u32 s1, s1, 0
	s_waitcnt lgkmcnt(0)
	v_lshlrev_b32_e32 v7, 16, v0
	v_and_b32_e32 v0, 0xffff0000, v0
	v_lshlrev_b32_e32 v8, 16, v1
	v_and_b32_e32 v1, 0xffff0000, v1
	v_lshlrev_b32_e32 v9, 16, v2
	v_and_b32_e32 v2, 0xffff0000, v2
	v_lshlrev_b32_e32 v10, 16, v3
	v_and_b32_e32 v3, 0xffff0000, v3
	s_lshl_b64 s[0:1], s[0:1], 11
	v_mul_f32_e32 v0, v6, v0
	v_mul_f32_e32 v1, v6, v1
	v_mul_f32_e32 v2, v6, v2
	v_mul_f32_e32 v3, v6, v3
	v_lshl_add_u64 v[4:5], v[4:5], 0, s[0:1]
	s_andn2_b64 vcc, exec, s[58:59]
	s_mov_b32 s64, s94
	s_mov_b32 s95, s91
	s_mov_b32 s61, s90
	s_mov_b32 s60, s89
	s_mov_b32 s63, s92
	s_mov_b32 s16, s93
	v_mul_f32_e32 v7, v6, v7
	v_mul_f32_e32 v8, v6, v8
	v_mul_f32_e32 v9, v6, v9
	v_mul_f32_e32 v10, v6, v10
	v_cvt_pk_bf16_f32 v0, v7, v0
	v_cvt_pk_bf16_f32 v1, v8, v1
	v_cvt_pk_bf16_f32 v2, v9, v2
	v_cvt_pk_bf16_f32 v3, v10, v3
	global_store_dwordx4 v[4:5], v[0:3], off
	s_barrier
	s_cbranch_vccz .LBB0_463

.LBB0_463:
	s_setprio 0
	s_waitcnt vmcnt(0)
	s_barrier
	s_and_saveexec_b64 s[0:1], s[14:15]
	s_cbranch_execz .LBB0_515
	s_add_i32 s4, 0, 0x25fe0
	v_mov_b32_e32 v0, s4
	s_waitcnt vmcnt(0) expcnt(0) lgkmcnt(0)
	ds_read_b32 v2, v0
	s_add_i32 s4, 0, 0x25fe4
	v_mov_b32_e32 v0, s4
	ds_read_b32 v0, v0
	s_waitcnt lgkmcnt(1)
	v_cmp_ne_u32_e32 vcc, 0, v2
	s_cbranch_vccnz .LBB0_479
	v_readlane_b32 s4, v230, 0
	s_mul_i32 s82, s43, s4
	s_add_u32 s4, s40, 0x4200
	s_addc_u32 s5, s41, 0
	s_add_u32 s6, s40, 0x4400
	s_addc_u32 s7, s41, 0
	s_add_u32 s16, s40, 0x4500
	s_addc_u32 s17, s41, 0
	s_add_u32 s36, s40, 0x4600
	s_addc_u32 s37, s41, 0
	s_add_u32 s44, s40, 0x4700
	s_addc_u32 s45, s41, 0
	s_add_u32 s46, s40, 0x4800
	s_addc_u32 s47, s41, 0
	s_add_u32 s48, s40, 0x4900
	s_addc_u32 s49, s41, 0
	s_add_u32 s52, s40, 0x4a00
	s_addc_u32 s53, s41, 0
	s_add_u32 s54, s40, 0x4b00
	s_addc_u32 s55, s41, 0
	s_add_u32 s56, s40, 0x4c00
	s_addc_u32 s57, s41, 0
	s_add_u32 s58, s40, 0x4d00
	s_addc_u32 s59, s41, 0
	s_add_u32 s60, s40, 0x4e00
	s_addc_u32 s61, s41, 0
	s_add_u32 s62, s40, 0x4f00
	s_addc_u32 s63, s41, 0
	s_add_u32 s64, s40, 0x5000
	s_addc_u32 s65, s41, 0
	s_add_u32 s66, s40, 0x5100
	s_addc_u32 s67, s41, 0
	s_add_u32 s68, s40, 0x5200
	s_addc_u32 s69, s41, 0
	s_add_u32 s70, s40, 0x5300
	s_mul_i32 s82, s82, s42
	s_addc_u32 s71, s41, 0
	s_mov_b32 s83, 1
	v_mov_b32_e32 v16, 0
	s_branch .LBB0_467

.LBB0_521:
	s_ashr_i32 s1, s16, 6
	s_mul_i32 s6, s1, 0x1400
	s_add_i32 s6, s6, 0
	s_add_i32 s18, s6, 0x1b000
	v_and_b32_e32 v14, 0x70, v0
	s_add_u32 s4, s22, s4
	s_movk_i32 s6, 0x380
	v_mov_b32_e32 v88, 0
	s_addc_u32 s5, s23, s5
	v_and_or_b32 v8, v0, s6, v14
	v_mov_b32_e32 v9, v88
	s_lshl_b32 s66, s1, 5
	v_lshl_add_u64 v[8:9], s[4:5], 0, v[8:9]
	s_add_i32 s4, s66, s63
	s_or_b32 s6, s4, 24
	s_ashr_i32 s7, s6, 31
	s_lshl_b64 s[6:7], s[6:7], 7
	v_lshl_add_u64 v[10:11], v[8:9], 0, s[6:7]
	s_or_b32 s6, s4, 16
	s_ashr_i32 s7, s6, 31
	s_lshl_b64 s[6:7], s[6:7], 7
	v_lshl_add_u64 v[12:13], v[8:9], 0, s[6:7]
	s_or_b32 s6, s4, 8
	s_ashr_i32 s7, s6, 31
	s_ashr_i32 s5, s4, 31
	s_lshl_b64 s[6:7], s[6:7], 7
	s_lshl_b64 s[4:5], s[4:5], 7
	global_load_dwordx4 v[136:139], v[10:11], off
	global_load_dwordx4 v[132:135], v[12:13], off
	v_lshl_add_u64 v[10:11], v[8:9], 0, s[6:7]
	v_lshl_add_u64 v[8:9], v[8:9], 0, s[4:5]
	s_lshl_b32 s4, s63, 7
	s_or_b32 s16, s4, 0x6000
	global_load_dwordx4 v[144:147], v[10:11], off
	global_load_dwordx4 v[140:143], v[8:9], off
	v_lshl_add_u64 v[8:9], v[2:3], 0, s[16:17]
	v_lshl_add_u64 v[10:11], v[4:5], 0, s[16:17]
	s_or_b32 s16, s4, 0x4000
	global_load_dwordx4 v[104:107], v[8:9], off nt
	global_load_dwordx4 v[100:103], v[10:11], off nt
	v_lshl_add_u64 v[8:9], v[4:5], 0, s[16:17]
	v_lshl_add_u64 v[10:11], v[2:3], 0, s[16:17]
	s_or_b32 s16, s4, 0x2000
	s_mov_b32 s5, s17
	global_load_dwordx4 v[108:111], v[8:9], off nt
	global_load_dwordx4 v[112:115], v[10:11], off nt
	v_lshl_add_u64 v[8:9], v[4:5], 0, s[16:17]
	v_lshl_add_u64 v[4:5], v[4:5], 0, s[4:5]
	v_lshl_add_u64 v[10:11], v[2:3], 0, s[16:17]
	global_load_dwordx4 v[116:119], v[8:9], off nt
	global_load_dwordx4 v[120:123], v[10:11], off nt
	v_lshl_add_u64 v[2:3], v[2:3], 0, s[4:5]
	global_load_dwordx4 v[124:127], v[4:5], off nt
	global_load_dwordx4 v[128:131], v[2:3], off nt
	v_and_b32_e32 v181, 31, v6
	v_bfe_u32 v15, v6, 5, 1
	v_lshl_add_u64 v[184:185], s[8:9], 0, v[0:1]
	v_lshl_add_u64 v[186:187], s[10:11], 0, v[0:1]
	s_movk_i32 s1, 0x90
	v_mov_b32_e32 v0, s18
	v_bfe_u32 v9, v6, 3, 3
	v_mad_u32_u24 v205, v181, s1, v0
	v_or_b32_e32 v0, 0x80, v181
	v_lshlrev_b32_e32 v1, 2, v15
	v_lshl_or_b32 v2, v9, 11, v14
	v_sub_u32_e32 v207, v0, v1
	v_mov_b32_e32 v3, v88
	v_bfe_u32 v0, v6, 2, 2
	v_lshl_add_u64 v[190:191], s[24:25], 0, v[2:3]
	v_lshl_add_u64 v[192:193], s[38:39], 0, v[2:3]
	v_or3_b32 v0, v0, v1, s66
	v_and_b32_e32 v1, 16, v6
	v_lshlrev_b32_e32 v2, 2, v6
	v_and_or_b32 v1, v2, 12, v1
	v_mul_lo_u32 v0, v0, s1
	v_lshlrev_b32_e32 v1, 1, v1
	v_add3_u32 v208, 0, v0, v1
	v_or_b32_e32 v0, s66, v181
	s_add_i32 s6, s66, 32
	v_mul_lo_u32 v12, v0, s1
	v_or_b32_e32 v0, s6, v181
	s_add_i32 s6, s66, 64
	v_mul_lo_u32 v13, v0, s1
	v_or_b32_e32 v0, s6, v181
	s_add_i32 s6, s66, 0x60
	v_add_u32_e32 v204, 0, v14
	v_add_u32_e32 v10, s18, v14
	v_lshl_or_b32 v4, v9, 7, v14
	v_mul_lo_u32 v14, v0, s1
	v_or_b32_e32 v0, s6, v181
	s_add_i32 s6, s66, 0x80
	v_mul_lo_u32 v16, v0, s1
	v_or_b32_e32 v0, s6, v181
	v_mul_lo_u32 v17, v0, s1
	v_mul_u32_u24_e32 v0, 0x240, v15
	v_lshlrev_b32_e32 v1, 1, v181
	v_add3_u32 v211, s18, v0, v1
	v_lshlrev_b32_e32 v0, 12, v6
	v_and_b32_e32 v0, 0x3000, v0
	v_mov_b32_e32 v1, v88
	v_lshl_add_u64 v[0:1], s[40:41], 0, v[0:1]
	s_mov_b64 s[6:7], 0x1b000000
	v_lshrrev_b32_e32 v8, 3, v6
	v_lshl_add_u64 v[194:195], v[0:1], 0, s[6:7]
	v_lshlrev_b32_e32 v0, 10, v6
	v_and_b32_e32 v7, 63, v6
	v_mov_b32_e32 v5, v88
	v_lshlrev_b32_e32 v206, 4, v15
	v_mul_lo_u32 v210, v8, s1
	v_and_b32_e32 v0, 0x3c00, v0
	v_mov_b32_e32 v1, v88
	v_lshl_add_u64 v[188:189], s[22:23], 0, v[4:5]
	v_add_u32_e32 v4, 0, v206
	v_cmp_gt_u32_e64 s[4:5], 32, v7
	v_mul_i32_i24_e32 v2, 0xffffff74, v181
	v_add_u32_e32 v3, 0x4800, v210
	v_add_u32_e32 v5, 0x6c00, v210
	v_add_u32_e32 v7, 0x9000, v210
	v_add_u32_e32 v8, 0xb400, v210
	v_mul_u32_u24_e32 v11, 0x90, v9
	v_lshl_add_u64 v[0:1], s[40:41], 0, v[0:1]
	s_mov_b64 s[6:7], 0x1b200000
	s_add_i32 s1, s2, s42
	s_mov_b32 s8, 2.0
	s_mov_b32 s10, 0x41000000
	s_mov_b32 s36, 0x41200000
	s_mov_b32 s44, 0x41800000
	s_mov_b32 s46, 0x41900000
	s_mov_b32 s48, 0x41c00000
	s_mov_b32 s52, 0x41d00000
	v_add_u32_e32 v209, 0xd800, v208
	v_lshl_add_u32 v212, v9, 2, s18
	v_lshl_add_u64 v[196:197], v[0:1], 0, s[6:7]
	s_lshl_b32 s67, s1, 8
	s_lshl_b32 s68, s42, 8
	v_add_u32_e32 v213, v204, v3
	v_add_u32_e32 v214, v204, v5
	v_add_u32_e32 v215, v204, v7
	v_add_u32_e32 v216, v204, v8
	s_mov_b32 s69, 0xc2fc0000
	v_add_u32_e32 v217, v4, v12
	s_movk_i32 s70, 0x7f
	s_mov_b32 s71, 0xff800000
	v_add_u32_e32 v218, v4, v13
	v_add_u32_e32 v219, v4, v14
	v_add_u32_e32 v220, v4, v16
	v_add_u32_e32 v221, v4, v17
	s_mov_b32 s9, 0x40400000
	s_mov_b32 s11, 0x41100000
	s_mov_b32 s37, 0x41300000
	s_mov_b32 s45, 0x41880000
	s_mov_b32 s47, 0x41980000
	s_mov_b32 s49, 0x41c80000
	s_mov_b32 s53, 0x41d80000
	s_movk_i32 s72, 0x81
	s_movk_i32 s73, 0x82
	s_movk_i32 s74, 0x83
	s_movk_i32 s75, 0x84
	s_movk_i32 s76, 0x89
	s_movk_i32 s77, 0x87
	s_movk_i32 s82, 0x8a
	s_movk_i32 s83, 0x8b
	s_movk_i32 s84, 0x8c
	s_movk_i32 s85, 0x91
	s_movk_i32 s86, 0x8f
	s_movk_i32 s87, 0x92
	s_movk_i32 s88, 0x93
	s_movk_i32 s89, 0x94
	s_movk_i32 s90, 0x99
	s_movk_i32 s91, 0x97
	s_movk_i32 s92, 0x9a
	s_movk_i32 s93, 0x9b
	s_movk_i32 s94, 0x9c
	v_mbcnt_hi_u32_b32 v222, -1, v183
	v_add_u32_e32 v223, v205, v2
	v_add_u32_e32 v224, v10, v11
	v_mov_b32_e32 v225, 0x42800000
	v_mov_b32_e32 v226, 0xff800000
	s_mov_b32 s95, s2
	s_mov_b32 s96, s63
	s_mov_b32 s97, s62
	s_waitcnt vmcnt(0)
	s_bitcmp1_b32 s33, 2
	s_cbranch_scc0 .Lprio_1
	s_setprio 1
.Lprio_1:
	s_branch .LBB0_523
.LBB0_522:
	s_or_b64 exec, exec, s[0:1]
	s_nop 15
	s_nop 7
	s_nop 15
	s_nop 7
	v_cvt_pk_bf16_f32 v0, v0, v16
	s_nop 4
	ds_write_b16 v211, v0
	ds_write_b16_d16_hi v211, v0 offset:64
	v_cvt_pk_bf16_f32 v0, v1, v17
	ds_write_b16 v211, v0 offset:144
	ds_write_b16_d16_hi v211, v0 offset:208
	v_cvt_pk_bf16_f32 v0, v2, v18
	ds_write_b16 v211, v0 offset:288
	ds_write_b16_d16_hi v211, v0 offset:352
	v_cvt_pk_bf16_f32 v0, v3, v19
	ds_write_b16 v211, v0 offset:432
	ds_write_b16_d16_hi v211, v0 offset:496
	v_cvt_pk_bf16_f32 v0, v4, v20
	ds_write_b16 v211, v0 offset:1152
	ds_write_b16_d16_hi v211, v0 offset:1216
	v_cvt_pk_bf16_f32 v0, v5, v21
	ds_write_b16 v211, v0 offset:1296
	ds_write_b16_d16_hi v211, v0 offset:1360
	v_cvt_pk_bf16_f32 v0, v6, v22
	ds_write_b16 v211, v0 offset:1440
	ds_write_b16_d16_hi v211, v0 offset:1504
	v_cvt_pk_bf16_f32 v0, v7, v23
	ds_write_b16 v211, v0 offset:1584
	ds_write_b16_d16_hi v211, v0 offset:1648
	v_cvt_pk_bf16_f32 v0, v8, v24
	ds_write_b16 v211, v0 offset:2304
	ds_write_b16_d16_hi v211, v0 offset:2368
	v_cvt_pk_bf16_f32 v0, v9, v25
	ds_write_b16 v211, v0 offset:2448
	ds_write_b16_d16_hi v211, v0 offset:2512
	v_cvt_pk_bf16_f32 v0, v10, v26
	ds_write_b16 v211, v0 offset:2592
	ds_write_b16_d16_hi v211, v0 offset:2656
	v_cvt_pk_bf16_f32 v0, v11, v27
	ds_write_b16 v211, v0 offset:2736
	ds_write_b16_d16_hi v211, v0 offset:2800
	v_cvt_pk_bf16_f32 v0, v12, v28
	ds_write_b16 v211, v0 offset:3456
	ds_write_b16_d16_hi v211, v0 offset:3520
	v_cvt_pk_bf16_f32 v0, v13, v29
	ds_write_b16 v211, v0 offset:3600
	ds_write_b16_d16_hi v211, v0 offset:3664
	v_cvt_pk_bf16_f32 v0, v14, v30
	ds_write_b16 v211, v0 offset:3744
	ds_write_b16_d16_hi v211, v0 offset:3808
	v_cvt_pk_bf16_f32 v0, v15, v31
	ds_write_b16 v211, v0 offset:3888
	ds_write_b16_d16_hi v211, v0 offset:3952
	s_waitcnt lgkmcnt(0)
	v_add_u32_e32 v14, 0x1000, v212
	ds_read_b128 v[2:5], v224
	ds_read2_b32 v[6:7], v14 offset0:128 offset1:160
	ds_read_b32 v12, v212 offset:4864
	s_waitcnt vmcnt(7)
	v_lshlrev_b32_e32 v9, 16, v176
	s_waitcnt vmcnt(6)
	v_lshlrev_b32_e32 v10, 16, v172
	s_waitcnt lgkmcnt(2)
	v_lshlrev_b32_e32 v8, 16, v2
	s_waitcnt lgkmcnt(1)
	v_pk_mul_f32 v[8:9], v[6:7], v[8:9]
	v_mov_b32_e32 v11, v6
	s_waitcnt lgkmcnt(0)
	v_fma_f32 v9, v12, v10, v9
	v_add_f32_e32 v13, v8, v9
	v_and_b32_e32 v9, 0xffff0000, v2
	v_and_b32_e32 v8, 0xffff0000, v176
	v_mov_b32_e32 v10, v7
	v_pk_mul_f32 v[8:9], v[10:11], v[8:9]
	v_and_b32_e32 v2, 0xffff0000, v172
	v_fma_f32 v2, v12, v2, v8
	v_add_f32_e32 v15, v2, v9
	v_lshlrev_b32_e32 v9, 16, v177
	v_lshlrev_b32_e32 v8, 16, v3
	v_pk_mul_f32 v[8:9], v[6:7], v[8:9]
	v_lshlrev_b32_e32 v2, 16, v173
	v_fma_f32 v2, v12, v2, v9
	v_add_f32_e32 v8, v8, v2
	v_and_b32_e32 v3, 0xffff0000, v3
	v_and_b32_e32 v2, 0xffff0000, v177
	v_pk_mul_f32 v[2:3], v[10:11], v[2:3]
	v_and_b32_e32 v9, 0xffff0000, v173
	v_fma_f32 v2, v12, v9, v2
	v_add_f32_e32 v9, v2, v3
	v_lshlrev_b32_e32 v3, 16, v178
	v_lshlrev_b32_e32 v2, 16, v4
	v_pk_mul_f32 v[2:3], v[6:7], v[2:3]
	v_lshlrev_b32_e32 v16, 16, v174
	v_fma_f32 v3, v12, v16, v3
	v_add_f32_e32 v16, v2, v3
	v_and_b32_e32 v3, 0xffff0000, v4
	v_and_b32_e32 v2, 0xffff0000, v178
	v_pk_mul_f32 v[2:3], v[10:11], v[2:3]
	v_and_b32_e32 v4, 0xffff0000, v174
	v_fma_f32 v2, v12, v4, v2
	v_add_f32_e32 v4, v2, v3
	v_lshlrev_b32_e32 v3, 16, v179
	v_lshlrev_b32_e32 v2, 16, v5
	v_pk_mul_f32 v[2:3], v[6:7], v[2:3]
	v_lshlrev_b32_e32 v6, 16, v175
	v_fma_f32 v3, v12, v6, v3
	v_add_f32_e32 v6, v2, v3
	v_and_b32_e32 v3, 0xffff0000, v5
	v_and_b32_e32 v2, 0xffff0000, v179
	v_pk_mul_f32 v[2:3], v[10:11], v[2:3]
	v_and_b32_e32 v5, 0xffff0000, v175
	v_fma_f32 v2, v12, v5, v2
	v_lshl_add_u64 v[0:1], v[192:193], 0, s[64:65]
	v_add_f32_e32 v5, v2, v3
	v_cvt_pk_bf16_f32 v2, v13, v15
	v_cvt_pk_bf16_f32 v3, v8, v9
	v_cvt_pk_bf16_f32 v4, v16, v4
	v_cvt_pk_bf16_f32 v5, v6, v5
	v_lshl_add_u64 v[10:11], v[0:1], 0, s[62:63]
	ds_read_b128 v[6:9], v224 offset:1152
	ds_read2_b32 v[12:13], v14 offset0:136 offset1:168
	global_store_dwordx4 v[10:11], v[2:5], off
	ds_read_b32 v10, v212 offset:4896
	s_waitcnt vmcnt(5)
	v_lshlrev_b32_e32 v15, 16, v165
	v_lshlrev_b32_e32 v3, 16, v168
	s_waitcnt lgkmcnt(2)
	v_lshlrev_b32_e32 v2, 16, v6
	s_waitcnt lgkmcnt(1)
	v_pk_mul_f32 v[2:3], v[12:13], v[2:3]
	v_lshlrev_b32_e32 v4, 16, v164
	s_waitcnt lgkmcnt(0)
	v_fma_f32 v3, v10, v4, v3
	v_add_f32_e32 v11, v2, v3
	v_and_b32_e32 v3, 0xffff0000, v6
	v_and_b32_e32 v2, 0xffff0000, v168
	v_mov_b32_e32 v4, v13
	v_mov_b32_e32 v5, v12
	v_pk_mul_f32 v[2:3], v[4:5], v[2:3]
	v_and_b32_e32 v6, 0xffff0000, v164
	v_fma_f32 v2, v10, v6, v2
	v_add_f32_e32 v6, v2, v3
	v_lshlrev_b32_e32 v3, 16, v169
	v_lshlrev_b32_e32 v2, 16, v7
	v_pk_mul_f32 v[2:3], v[12:13], v[2:3]
	v_lshlrev_b32_e32 v16, 16, v166
	v_fma_f32 v3, v10, v15, v3
	v_add_f32_e32 v15, v2, v3
	v_and_b32_e32 v3, 0xffff0000, v7
	v_and_b32_e32 v2, 0xffff0000, v169
	v_pk_mul_f32 v[2:3], v[4:5], v[2:3]
	v_and_b32_e32 v7, 0xffff0000, v165
	v_fma_f32 v2, v10, v7, v2
	v_add_f32_e32 v7, v2, v3
	v_lshlrev_b32_e32 v3, 16, v170
	v_lshlrev_b32_e32 v2, 16, v8
	v_pk_mul_f32 v[2:3], v[12:13], v[2:3]
	s_add_i32 s67, s67, s68
	v_fma_f32 v3, v10, v16, v3
	v_add_f32_e32 v16, v2, v3
	v_and_b32_e32 v3, 0xffff0000, v8
	v_and_b32_e32 v2, 0xffff0000, v170
	v_pk_mul_f32 v[2:3], v[4:5], v[2:3]
	v_and_b32_e32 v8, 0xffff0000, v166
	v_fma_f32 v2, v10, v8, v2
	v_add_f32_e32 v8, v2, v3
	v_lshlrev_b32_e32 v3, 16, v171
	v_lshlrev_b32_e32 v2, 16, v9
	v_pk_mul_f32 v[2:3], v[12:13], v[2:3]
	v_lshlrev_b32_e32 v12, 16, v167
	v_fma_f32 v3, v10, v12, v3
	v_add_f32_e32 v12, v2, v3
	v_and_b32_e32 v3, 0xffff0000, v9
	v_and_b32_e32 v2, 0xffff0000, v171
	v_pk_mul_f32 v[2:3], v[4:5], v[2:3]
	v_and_b32_e32 v4, 0xffff0000, v167
	v_fma_f32 v2, v10, v4, v2
	v_add_f32_e32 v5, v2, v3
	v_cvt_pk_bf16_f32 v2, v11, v6
	v_cvt_pk_bf16_f32 v3, v15, v7
	v_cvt_pk_bf16_f32 v4, v16, v8
	v_cvt_pk_bf16_f32 v5, v12, v5
	v_lshl_add_u64 v[10:11], v[0:1], 0, s[60:61]
	ds_read_b128 v[6:9], v224 offset:2304
	ds_read2_b32 v[12:13], v14 offset0:144 offset1:176
	global_store_dwordx4 v[10:11], v[2:5], off
	ds_read_b32 v10, v212 offset:4928
	s_waitcnt vmcnt(4)
	v_lshlrev_b32_e32 v15, 16, v157
	v_lshlrev_b32_e32 v3, 16, v160
	s_waitcnt lgkmcnt(2)
	v_lshlrev_b32_e32 v2, 16, v6
	s_waitcnt lgkmcnt(1)
	v_pk_mul_f32 v[2:3], v[12:13], v[2:3]
	v_lshlrev_b32_e32 v4, 16, v156
	s_waitcnt lgkmcnt(0)
	v_fma_f32 v3, v10, v4, v3
	v_add_f32_e32 v11, v2, v3
	v_and_b32_e32 v3, 0xffff0000, v6
	v_and_b32_e32 v2, 0xffff0000, v160
	v_mov_b32_e32 v4, v13
	v_mov_b32_e32 v5, v12
	v_pk_mul_f32 v[2:3], v[4:5], v[2:3]
	v_and_b32_e32 v6, 0xffff0000, v156
	v_fma_f32 v2, v10, v6, v2
	v_add_f32_e32 v6, v2, v3
	v_lshlrev_b32_e32 v3, 16, v161
	v_lshlrev_b32_e32 v2, 16, v7
	v_pk_mul_f32 v[2:3], v[12:13], v[2:3]
	v_lshlrev_b32_e32 v16, 16, v158
	v_fma_f32 v3, v10, v15, v3
	v_add_f32_e32 v15, v2, v3
	v_and_b32_e32 v3, 0xffff0000, v7
	v_and_b32_e32 v2, 0xffff0000, v161
	v_pk_mul_f32 v[2:3], v[4:5], v[2:3]
	v_and_b32_e32 v7, 0xffff0000, v157
	v_fma_f32 v2, v10, v7, v2
	v_add_f32_e32 v7, v2, v3
	v_lshlrev_b32_e32 v3, 16, v162
	v_lshlrev_b32_e32 v2, 16, v8
	v_pk_mul_f32 v[2:3], v[12:13], v[2:3]
	s_andn2_b64 vcc, exec, s[56:57]
	v_fma_f32 v3, v10, v16, v3
	v_add_f32_e32 v16, v2, v3
	v_and_b32_e32 v3, 0xffff0000, v8
	v_and_b32_e32 v2, 0xffff0000, v162
	v_pk_mul_f32 v[2:3], v[4:5], v[2:3]
	v_and_b32_e32 v8, 0xffff0000, v158
	v_fma_f32 v2, v10, v8, v2
	v_add_f32_e32 v8, v2, v3
	v_lshlrev_b32_e32 v3, 16, v163
	v_lshlrev_b32_e32 v2, 16, v9
	v_pk_mul_f32 v[2:3], v[12:13], v[2:3]
	v_lshlrev_b32_e32 v12, 16, v159
	v_fma_f32 v3, v10, v12, v3
	v_add_f32_e32 v12, v2, v3
	v_and_b32_e32 v3, 0xffff0000, v9
	v_and_b32_e32 v2, 0xffff0000, v163
	v_pk_mul_f32 v[2:3], v[4:5], v[2:3]
	v_and_b32_e32 v4, 0xffff0000, v159
	v_fma_f32 v2, v10, v4, v2
	v_add_f32_e32 v5, v2, v3
	v_cvt_pk_bf16_f32 v2, v11, v6
	v_cvt_pk_bf16_f32 v3, v15, v7
	v_cvt_pk_bf16_f32 v4, v16, v8
	v_cvt_pk_bf16_f32 v5, v12, v5
	v_lshl_add_u64 v[10:11], v[0:1], 0, s[58:59]
	ds_read_b128 v[6:9], v224 offset:3456
	ds_read2_b32 v[12:13], v14 offset0:152 offset1:184
	global_store_dwordx4 v[10:11], v[2:5], off
	ds_read_b32 v10, v212 offset:4960
	s_waitcnt vmcnt(3)
	v_lshlrev_b32_e32 v14, 16, v149
	v_lshlrev_b32_e32 v3, 16, v152
	s_waitcnt lgkmcnt(2)
	v_lshlrev_b32_e32 v2, 16, v6
	s_waitcnt lgkmcnt(1)
	v_pk_mul_f32 v[2:3], v[12:13], v[2:3]
	v_lshlrev_b32_e32 v4, 16, v148
	s_waitcnt lgkmcnt(0)
	v_fma_f32 v3, v10, v4, v3
	v_add_f32_e32 v11, v2, v3
	v_and_b32_e32 v3, 0xffff0000, v6
	v_and_b32_e32 v2, 0xffff0000, v152
	v_mov_b32_e32 v4, v13
	v_mov_b32_e32 v5, v12
	v_pk_mul_f32 v[2:3], v[4:5], v[2:3]
	v_and_b32_e32 v6, 0xffff0000, v148
	v_fma_f32 v2, v10, v6, v2
	v_add_f32_e32 v6, v2, v3
	v_lshlrev_b32_e32 v3, 16, v153
	v_lshlrev_b32_e32 v2, 16, v7
	v_pk_mul_f32 v[2:3], v[12:13], v[2:3]
	v_lshlrev_b32_e32 v15, 16, v150
	v_fma_f32 v3, v10, v14, v3
	v_add_f32_e32 v14, v2, v3
	v_and_b32_e32 v3, 0xffff0000, v7
	v_and_b32_e32 v2, 0xffff0000, v153
	v_pk_mul_f32 v[2:3], v[4:5], v[2:3]
	v_and_b32_e32 v7, 0xffff0000, v149
	v_fma_f32 v2, v10, v7, v2
	v_add_f32_e32 v7, v2, v3
	v_lshlrev_b32_e32 v3, 16, v154
	v_lshlrev_b32_e32 v2, 16, v8
	v_pk_mul_f32 v[2:3], v[12:13], v[2:3]
	v_lshl_add_u64 v[0:1], v[0:1], 0, s[6:7]
	v_fma_f32 v3, v10, v15, v3
	v_add_f32_e32 v15, v2, v3
	v_and_b32_e32 v3, 0xffff0000, v8
	v_and_b32_e32 v2, 0xffff0000, v154
	v_pk_mul_f32 v[2:3], v[4:5], v[2:3]
	v_and_b32_e32 v8, 0xffff0000, v150
	v_fma_f32 v2, v10, v8, v2
	v_add_f32_e32 v8, v2, v3
	v_lshlrev_b32_e32 v3, 16, v155
	v_lshlrev_b32_e32 v2, 16, v9
	v_pk_mul_f32 v[2:3], v[12:13], v[2:3]
	v_lshlrev_b32_e32 v12, 16, v151
	v_fma_f32 v3, v10, v12, v3
	v_add_f32_e32 v12, v2, v3
	v_and_b32_e32 v3, 0xffff0000, v9
	v_and_b32_e32 v2, 0xffff0000, v155
	v_pk_mul_f32 v[2:3], v[4:5], v[2:3]
	v_and_b32_e32 v4, 0xffff0000, v151
	v_fma_f32 v2, v10, v4, v2
	v_add_f32_e32 v5, v2, v3
	s_mov_b32 s63, s96
	s_mov_b32 s62, s97
	s_mov_b32 s0, s54
	v_cvt_pk_bf16_f32 v2, v11, v6
	v_cvt_pk_bf16_f32 v3, v14, v7
	v_cvt_pk_bf16_f32 v4, v15, v8
	v_cvt_pk_bf16_f32 v5, v12, v5
	global_store_dwordx4 v[0:1], v[2:5], off
	s_barrier
	s_cbranch_vccz .LBB0_532

.LBB0_532:
	s_setprio 0
	s_waitcnt vmcnt(0)
	s_barrier
	s_and_saveexec_b64 s[0:1], s[14:15]
	s_cbranch_execz .LBB0_584
	s_add_i32 s4, 0, 0x25fe0
	v_mov_b32_e32 v0, s4
	s_waitcnt vmcnt(0) expcnt(0) lgkmcnt(0)
	ds_read_b32 v2, v0
	s_add_i32 s4, 0, 0x25fe4
	v_mov_b32_e32 v0, s4
	ds_read_b32 v0, v0
	s_waitcnt lgkmcnt(1)
	v_cmp_ne_u32_e32 vcc, 0, v2
	s_cbranch_vccnz .LBB0_548
	v_readlane_b32 s4, v230, 0
	s_mul_i32 s74, s43, s4
	s_add_u32 s4, s40, 0x4200
	s_addc_u32 s5, s41, 0
	s_add_u32 s6, s40, 0x4400
	s_addc_u32 s7, s41, 0
	s_add_u32 s8, s40, 0x4500
	s_addc_u32 s9, s41, 0
	s_add_u32 s10, s40, 0x4600
	s_addc_u32 s11, s41, 0
	s_add_u32 s16, s40, 0x4700
	s_addc_u32 s17, s41, 0
	s_add_u32 s36, s40, 0x4800
	s_addc_u32 s37, s41, 0
	s_add_u32 s44, s40, 0x4900
	s_addc_u32 s45, s41, 0
	s_add_u32 s46, s40, 0x4a00
	s_addc_u32 s47, s41, 0
	s_add_u32 s48, s40, 0x4b00
	s_addc_u32 s49, s41, 0
	s_add_u32 s52, s40, 0x4c00
	s_addc_u32 s53, s41, 0
	s_add_u32 s54, s40, 0x4d00
	s_addc_u32 s55, s41, 0
	s_add_u32 s56, s40, 0x4e00
	s_addc_u32 s57, s41, 0
	s_add_u32 s58, s40, 0x4f00
	s_addc_u32 s59, s41, 0
	s_add_u32 s60, s40, 0x5000
	s_addc_u32 s61, s41, 0
	s_add_u32 s62, s40, 0x5100
	s_addc_u32 s63, s41, 0
	s_add_u32 s64, s40, 0x5200
	s_addc_u32 s65, s41, 0
	s_add_u32 s66, s40, 0x5300
	s_mul_i32 s74, s74, s42
	s_addc_u32 s67, s41, 0
	s_mov_b32 s75, 1
	v_mov_b32_e32 v16, 0
	s_branch .LBB0_536

.LBB0_1227:
	s_lshl_b64 s[12:13], s[16:17], 19
	s_ashr_i32 s17, s18, 6
	s_mul_i32 s18, s17, 0x1400
	s_add_i32 s18, s18, 0
	s_add_i32 s45, s18, 0x1b000
	s_lshl_b32 s18, s88, 7
	s_mov_b32 s19, s1
	v_lshl_add_u64 v[8:9], v[4:5], 0, s[18:19]
	v_lshl_add_u64 v[10:11], v[2:3], 0, s[18:19]
	s_or_b32 s36, s18, 0x2000
	s_mov_b32 s37, s1
	s_lshl_b32 s44, s0, 22
	global_load_dwordx4 v[98:101], v[8:9], off nt
	global_load_dwordx4 v[102:105], v[10:11], off nt
	v_lshl_add_u64 v[8:9], v[4:5], 0, s[36:37]
	v_lshl_add_u64 v[10:11], v[2:3], 0, s[36:37]
	s_or_b32 s36, s18, 0x4000
	s_or_b32 s18, s18, 0x6000
	s_lshl_b32 s63, s17, 5
	s_add_u32 s17, s22, s44
	global_load_dwordx4 v[106:109], v[8:9], off nt
	global_load_dwordx4 v[110:113], v[10:11], off nt
	v_lshl_add_u64 v[8:9], v[4:5], 0, s[36:37]
	v_lshl_add_u64 v[10:11], v[2:3], 0, s[36:37]
	v_lshl_add_u64 v[4:5], v[4:5], 0, s[18:19]
	v_lshl_add_u64 v[2:3], v[2:3], 0, s[18:19]
	s_addc_u32 s18, s23, 0
	global_load_dwordx4 v[114:117], v[8:9], off nt
	global_load_dwordx4 v[118:121], v[10:11], off nt
	s_add_u32 s12, s17, s12
	v_and_b32_e32 v10, 0x70, v0
	s_movk_i32 s17, 0x380
	v_mov_b32_e32 v96, 0
	global_load_dwordx4 v[126:129], v[4:5], off nt
	global_load_dwordx4 v[122:125], v[2:3], off nt
	s_addc_u32 s13, s18, s13
	v_and_or_b32 v2, v0, s17, v10
	v_mov_b32_e32 v3, v96
	v_lshl_add_u64 v[2:3], s[12:13], 0, v[2:3]
	s_add_i32 s12, s63, s88
	s_or_b32 s18, s12, 24
	s_ashr_i32 s19, s18, 31
	s_lshl_b64 s[18:19], s[18:19], 7
	v_lshl_add_u64 v[4:5], v[2:3], 0, s[18:19]
	s_or_b32 s18, s12, 16
	s_ashr_i32 s19, s18, 31
	s_lshl_b64 s[18:19], s[18:19], 7
	v_lshl_add_u64 v[8:9], v[2:3], 0, s[18:19]
	s_or_b32 s18, s12, 8
	s_ashr_i32 s19, s18, 31
	s_lshl_b64 s[18:19], s[18:19], 7
	s_ashr_i32 s13, s12, 31
	global_load_dwordx4 v[138:141], v[4:5], off
	global_load_dwordx4 v[142:145], v[8:9], off
	v_lshl_add_u64 v[4:5], v[2:3], 0, s[18:19]
	s_lshl_b64 s[12:13], s[12:13], 7
	v_lshl_add_u64 v[2:3], v[2:3], 0, s[12:13]
	global_load_dwordx4 v[130:133], v[4:5], off
	global_load_dwordx4 v[134:137], v[2:3], off
	v_and_b32_e32 v12, 31, v6
	v_bfe_u32 v13, v6, 5, 1
	v_lshl_add_u64 v[162:163], s[30:31], 0, v[0:1]
	v_lshl_add_u64 v[164:165], s[10:11], 0, v[0:1]
	s_movk_i32 s64, 0x90
	v_mov_b32_e32 v0, s45
	v_bfe_u32 v3, v6, 3, 3
	v_mad_u32_u24 v167, v12, s64, v0
	v_or_b32_e32 v0, 0x80, v12
	v_lshlrev_b32_e32 v1, 2, v13
	v_bfe_u32 v5, v6, 2, 2
	s_add_i32 s12, s63, 32
	v_and_b32_e32 v7, 63, v6
	v_lshrrev_b32_e32 v2, 3, v6
	v_add_u32_e32 v166, 0, v10
	v_add_u32_e32 v4, s45, v10
	v_lshl_or_b32 v158, v3, 11, v10
	v_lshl_or_b32 v160, v3, 7, v10
	v_sub_u32_e32 v169, v0, v1
	v_or3_b32 v1, v5, v1, s63
	v_and_b32_e32 v5, 16, v6
	v_lshlrev_b32_e32 v6, 2, v6
	v_or_b32_e32 v10, s12, v12
	s_add_i32 s12, s63, 64
	v_and_or_b32 v5, v6, 12, v5
	v_or_b32_e32 v11, s12, v12
	s_add_i32 s12, s63, 0x60
	v_mul_lo_u32 v1, v1, s64
	v_lshlrev_b32_e32 v5, 1, v5
	v_or_b32_e32 v14, s12, v12
	s_add_i32 s12, s63, 0x80
	v_lshlrev_b32_e32 v168, 4, v13
	v_add3_u32 v170, 0, v1, v5
	v_mul_i32_i24_e32 v1, 0xffffff74, v12
	v_mul_lo_u32 v172, v2, s64
	v_or_b32_e32 v9, s63, v12
	v_or_b32_e32 v15, s12, v12
	v_mul_u32_u24_e32 v13, 0x240, v13
	v_lshlrev_b32_e32 v12, 1, v12
	v_add_u32_e32 v0, 0, v168
	v_cmp_gt_u32_e64 s[10:11], 32, v7
	v_add_u32_e32 v2, 0x4800, v172
	v_add_u32_e32 v5, 0x6c00, v172
	v_add_u32_e32 v6, 0x9000, v172
	v_add_u32_e32 v7, 0xb400, v172
	v_mul_u32_u24_e32 v8, 0x90, v3
	v_mul_lo_u32 v9, v9, s64
	v_mul_lo_u32 v10, v10, s64
	v_mul_lo_u32 v11, v11, s64
	v_mul_lo_u32 v14, v14, s64
	v_mul_lo_u32 v15, v15, s64
	v_add3_u32 v173, s45, v13, v12
	v_lshl_add_u32 v174, v3, 2, s45
	s_mov_b32 s18, 2.0
	s_mov_b32 s30, 0x41000000
	s_mov_b32 s36, 0x41200000
	s_mov_b32 s44, 0x41800000
	s_mov_b32 s46, 0x41900000
	s_mov_b32 s48, 0x41c00000
	s_mov_b32 s52, 0x41d00000
	v_mov_b32_e32 v161, v96
	s_movk_i32 s65, 0x80
	v_add_u32_e32 v171, 0xd800, v170
	v_mov_b32_e32 v159, v96
	s_mov_b64 s[54:55], -1
	v_add_u32_e32 v175, v166, v2
	v_add_u32_e32 v176, v166, v5
	v_add_u32_e32 v177, v166, v6
	v_add_u32_e32 v178, v166, v7
	s_mov_b32 s66, 0xc2fc0000
	v_add_u32_e32 v179, v0, v9
	s_mov_b32 s67, 0xff800000
	v_add_u32_e32 v181, v0, v10
	v_add_u32_e32 v184, v0, v11
	v_add_u32_e32 v185, v0, v14
	v_add_u32_e32 v186, v0, v15
	s_mov_b32 s19, 0x40400000
	s_mov_b32 s31, 0x41100000
	s_mov_b32 s37, 0x41300000
	s_mov_b32 s45, 0x41880000
	s_mov_b32 s47, 0x41980000
	s_mov_b32 s49, 0x41c80000
	s_mov_b32 s53, 0x41d80000
	s_movk_i32 s68, 0x81
	s_movk_i32 s69, 0x82
	s_movk_i32 s70, 0x83
	s_movk_i32 s71, 0x88
	s_movk_i32 s72, 0x89
	s_movk_i32 s73, 0x8a
	s_movk_i32 s74, 0x8b
	s_movk_i32 s75, 0x91
	s_movk_i32 s76, 0x92
	s_movk_i32 s77, 0x93
	s_movk_i32 s82, 0x98
	s_movk_i32 s83, 0x99
	s_movk_i32 s84, 0x9a
	s_movk_i32 s85, 0x9b
	v_mbcnt_hi_u32_b32 v187, -1, v183
	v_add_u32_e32 v188, v167, v1
	v_add_u32_e32 v189, v4, v8
	v_mov_b32_e32 v190, 0x42800000
	v_mov_b32_e32 v191, 0xff800000
	s_waitcnt vmcnt(0)
	s_bitcmp1_b32 s33, 2
	s_cbranch_scc0 .Lprio_2
	s_setprio 1
.Lprio_2:
	s_branch .LBB0_1229
.LBB0_1228:
	s_or_b64 exec, exec, s[60:61]
	s_nop 15
	s_nop 7
	s_nop 15
	s_nop 7
	v_cvt_pk_bf16_f32 v0, v0, v16
	s_nop 4
	ds_write_b16 v173, v0
	ds_write_b16_d16_hi v173, v0 offset:64
	v_cvt_pk_bf16_f32 v0, v1, v17
	ds_write_b16 v173, v0 offset:144
	ds_write_b16_d16_hi v173, v0 offset:208
	v_cvt_pk_bf16_f32 v0, v2, v18
	ds_write_b16 v173, v0 offset:288
	ds_write_b16_d16_hi v173, v0 offset:352
	v_cvt_pk_bf16_f32 v0, v3, v19
	ds_write_b16 v173, v0 offset:432
	ds_write_b16_d16_hi v173, v0 offset:496
	v_cvt_pk_bf16_f32 v0, v4, v20
	ds_write_b16 v173, v0 offset:1152
	ds_write_b16_d16_hi v173, v0 offset:1216
	v_cvt_pk_bf16_f32 v0, v5, v21
	ds_write_b16 v173, v0 offset:1296
	ds_write_b16_d16_hi v173, v0 offset:1360
	v_cvt_pk_bf16_f32 v0, v6, v22
	ds_write_b16 v173, v0 offset:1440
	ds_write_b16_d16_hi v173, v0 offset:1504
	v_cvt_pk_bf16_f32 v0, v7, v23
	ds_write_b16 v173, v0 offset:1584
	ds_write_b16_d16_hi v173, v0 offset:1648
	v_cvt_pk_bf16_f32 v0, v8, v24
	ds_write_b16 v173, v0 offset:2304
	ds_write_b16_d16_hi v173, v0 offset:2368
	v_cvt_pk_bf16_f32 v0, v9, v25
	ds_write_b16 v173, v0 offset:2448
	ds_write_b16_d16_hi v173, v0 offset:2512
	v_cvt_pk_bf16_f32 v0, v10, v26
	ds_write_b16 v173, v0 offset:2592
	ds_write_b16_d16_hi v173, v0 offset:2656
	v_cvt_pk_bf16_f32 v0, v11, v27
	ds_write_b16 v173, v0 offset:2736
	ds_write_b16_d16_hi v173, v0 offset:2800
	v_cvt_pk_bf16_f32 v0, v12, v28
	ds_write_b16 v173, v0 offset:3456
	ds_write_b16_d16_hi v173, v0 offset:3520
	v_cvt_pk_bf16_f32 v0, v13, v29
	ds_write_b16 v173, v0 offset:3600
	ds_write_b16_d16_hi v173, v0 offset:3664
	v_cvt_pk_bf16_f32 v0, v14, v30
	ds_write_b16 v173, v0 offset:3744
	ds_write_b16_d16_hi v173, v0 offset:3808
	v_cvt_pk_bf16_f32 v0, v15, v31
	ds_write_b16 v173, v0 offset:3888
	ds_write_b16_d16_hi v173, v0 offset:3952
	s_waitcnt lgkmcnt(0)
	ds_read_b32 v4, v174 offset:4608
	ds_read_b128 v[0:3], v189
	s_ashr_i32 s17, s16, 31
	s_lshl_b32 s0, s0, 7
	s_lshl_b64 s[16:17], s[16:17], 23
	s_add_u32 s13, s38, s16
	s_waitcnt lgkmcnt(0)
	v_lshlrev_b32_e32 v5, 16, v0
	v_and_b32_e32 v0, 0xffff0000, v0
	v_lshlrev_b32_e32 v6, 16, v1
	v_and_b32_e32 v1, 0xffff0000, v1
	v_lshlrev_b32_e32 v7, 16, v2
	v_and_b32_e32 v2, 0xffff0000, v2
	v_lshlrev_b32_e32 v10, 16, v3
	v_and_b32_e32 v3, 0xffff0000, v3
	v_mul_f32_e32 v5, v4, v5
	v_mul_f32_e32 v0, v4, v0
	v_mul_f32_e32 v6, v4, v6
	v_mul_f32_e32 v1, v4, v1
	v_mul_f32_e32 v7, v4, v7
	v_mul_f32_e32 v2, v4, v2
	v_mul_f32_e32 v3, v4, v3
	s_addc_u32 s17, s39, s17
	v_mul_f32_e32 v10, v4, v10
	v_cvt_pk_bf16_f32 v0, v5, v0
	v_cvt_pk_bf16_f32 v1, v6, v1
	v_cvt_pk_bf16_f32 v2, v7, v2
	v_cvt_pk_bf16_f32 v3, v10, v3
	ds_read_b32 v12, v174 offset:4640
	ds_read_b128 v[4:7], v189 offset:1152
	s_add_u32 s16, s13, s0
	s_addc_u32 s17, s17, 0
	s_ashr_i32 s13, s12, 31
	v_lshl_add_u64 v[8:9], s[16:17], 0, v[158:159]
	s_lshl_b64 s[16:17], s[12:13], 11
	v_lshl_add_u64 v[10:11], v[8:9], 0, s[16:17]
	global_store_dwordx4 v[10:11], v[0:3], off
	s_or_b32 s16, s12, 8
	s_ashr_i32 s17, s16, 31
	s_waitcnt lgkmcnt(0)
	v_lshlrev_b32_e32 v0, 16, v4
	v_and_b32_e32 v1, 0xffff0000, v4
	v_lshlrev_b32_e32 v2, 16, v5
	v_and_b32_e32 v3, 0xffff0000, v5
	v_lshlrev_b32_e32 v4, 16, v6
	v_and_b32_e32 v5, 0xffff0000, v6
	v_lshlrev_b32_e32 v6, 16, v7
	v_and_b32_e32 v7, 0xffff0000, v7
	v_mul_f32_e32 v0, v12, v0
	v_mul_f32_e32 v1, v12, v1
	v_mul_f32_e32 v2, v12, v2
	v_mul_f32_e32 v3, v12, v3
	v_mul_f32_e32 v4, v12, v4
	v_mul_f32_e32 v5, v12, v5
	v_mul_f32_e32 v6, v12, v6
	v_mul_f32_e32 v7, v12, v7
	v_cvt_pk_bf16_f32 v0, v0, v1
	v_cvt_pk_bf16_f32 v1, v2, v3
	v_cvt_pk_bf16_f32 v2, v4, v5
	v_cvt_pk_bf16_f32 v3, v6, v7
	ds_read_b32 v12, v174 offset:4672
	ds_read_b128 v[4:7], v189 offset:2304
	s_lshl_b64 s[16:17], s[16:17], 11
	v_lshl_add_u64 v[10:11], v[8:9], 0, s[16:17]
	global_store_dwordx4 v[10:11], v[0:3], off
	s_or_b32 s16, s12, 16
	s_ashr_i32 s17, s16, 31
	s_waitcnt lgkmcnt(0)
	v_lshlrev_b32_e32 v0, 16, v4
	v_and_b32_e32 v1, 0xffff0000, v4
	v_lshlrev_b32_e32 v2, 16, v5
	v_and_b32_e32 v3, 0xffff0000, v5
	v_lshlrev_b32_e32 v4, 16, v6
	v_and_b32_e32 v5, 0xffff0000, v6
	v_lshlrev_b32_e32 v6, 16, v7
	v_and_b32_e32 v7, 0xffff0000, v7
	v_mul_f32_e32 v0, v12, v0
	v_mul_f32_e32 v1, v12, v1
	v_mul_f32_e32 v2, v12, v2
	v_mul_f32_e32 v3, v12, v3
	v_mul_f32_e32 v4, v12, v4
	v_mul_f32_e32 v5, v12, v5
	v_mul_f32_e32 v6, v12, v6
	v_mul_f32_e32 v7, v12, v7
	v_cvt_pk_bf16_f32 v0, v0, v1
	v_cvt_pk_bf16_f32 v1, v2, v3
	v_cvt_pk_bf16_f32 v2, v4, v5
	v_cvt_pk_bf16_f32 v3, v6, v7
	ds_read_b32 v12, v174 offset:4704
	ds_read_b128 v[4:7], v189 offset:3456
	s_lshl_b64 s[16:17], s[16:17], 11
	v_lshl_add_u64 v[10:11], v[8:9], 0, s[16:17]
	s_or_b32 s12, s12, 24
	global_store_dwordx4 v[10:11], v[0:3], off
	s_ashr_i32 s13, s12, 31
	s_lshl_b64 s[12:13], s[12:13], 11
	s_waitcnt lgkmcnt(0)
	v_lshlrev_b32_e32 v0, 16, v4
	v_and_b32_e32 v1, 0xffff0000, v4
	v_lshlrev_b32_e32 v2, 16, v5
	v_and_b32_e32 v3, 0xffff0000, v5
	v_lshlrev_b32_e32 v4, 16, v6
	v_and_b32_e32 v5, 0xffff0000, v6
	v_mul_f32_e32 v0, v12, v0
	v_mul_f32_e32 v1, v12, v1
	v_mul_f32_e32 v2, v12, v2
	v_mul_f32_e32 v4, v12, v4
	v_mul_f32_e32 v5, v12, v5
	v_mul_f32_e32 v3, v12, v3
	v_lshlrev_b32_e32 v6, 16, v7
	v_and_b32_e32 v7, 0xffff0000, v7
	v_cvt_pk_bf16_f32 v0, v0, v1
	v_cvt_pk_bf16_f32 v1, v2, v3
	v_cvt_pk_bf16_f32 v2, v4, v5
	v_lshl_add_u64 v[4:5], v[8:9], 0, s[12:13]
	s_add_i32 s62, s62, 1
	s_andn2_b64 vcc, exec, s[58:59]
	s_mov_b32 s16, s56
	s_mov_b32 s0, s87
	s_mov_b32 s88, s86
	v_mul_f32_e32 v6, v12, v6
	v_mul_f32_e32 v7, v12, v7
	v_cvt_pk_bf16_f32 v3, v6, v7
	global_store_dwordx4 v[4:5], v[0:3], off
	s_barrier
	s_cbranch_vccz .LBB0_1242

.LBB0_1242:
	s_setprio 0
	s_waitcnt vmcnt(0)
	s_barrier
	s_and_saveexec_b64 s[0:1], s[14:15]
	s_cbranch_execz .LBB0_1294
	s_add_i32 s10, 0, 0x25fe0
	v_mov_b32_e32 v0, s10
	s_waitcnt vmcnt(0) expcnt(0) lgkmcnt(0)
	ds_read_b32 v2, v0
	s_add_i32 s10, 0, 0x25fe4
	v_mov_b32_e32 v0, s10
	ds_read_b32 v0, v0
	s_waitcnt lgkmcnt(1)
	v_cmp_ne_u32_e32 vcc, 0, v2
	s_cbranch_vccnz .LBB0_1258
	v_readlane_b32 s10, v230, 0
	s_mul_i32 s72, s43, s10
	s_add_u32 s10, s40, 0x4200
	s_addc_u32 s11, s41, 0
	s_add_u32 s12, s40, 0x4400
	s_addc_u32 s13, s41, 0
	s_add_u32 s16, s40, 0x4500
	s_addc_u32 s17, s41, 0
	s_add_u32 s18, s40, 0x4600
	s_addc_u32 s19, s41, 0
	s_add_u32 s30, s40, 0x4700
	s_addc_u32 s31, s41, 0
	s_add_u32 s36, s40, 0x4800
	s_addc_u32 s37, s41, 0
	s_add_u32 s44, s40, 0x4900
	s_addc_u32 s45, s41, 0
	s_add_u32 s46, s40, 0x4a00
	s_addc_u32 s47, s41, 0
	s_add_u32 s48, s40, 0x4b00
	s_addc_u32 s49, s41, 0
	s_add_u32 s50, s40, 0x4c00
	s_addc_u32 s51, s41, 0
	s_add_u32 s52, s40, 0x4d00
	s_addc_u32 s53, s41, 0
	s_add_u32 s54, s40, 0x4e00
	s_addc_u32 s55, s41, 0
	s_add_u32 s56, s40, 0x4f00
	s_addc_u32 s57, s41, 0
	s_add_u32 s58, s40, 0x5000
	s_addc_u32 s59, s41, 0
	s_add_u32 s60, s40, 0x5100
	s_addc_u32 s61, s41, 0
	s_add_u32 s62, s40, 0x5200
	s_addc_u32 s63, s41, 0
	s_add_u32 s64, s40, 0x5300
	s_mul_i32 s72, s72, s42
	s_addc_u32 s65, s41, 0
	s_mov_b32 s73, 1
	v_mov_b32_e32 v16, 0
	s_branch .LBB0_1246
